# rowwise residual+adaLN phases 17 and 20 hand-rewritten: scalar row decode, next-row prefetch, all table loads issued together, no store drains
# speedup vs baseline: 1.0372x; 1.0112x over previous
; DI int get_tid() { int t = threadIdx.x; asm volatile("" : "+v"(t)); return t; }
; DI int get_bid() { int t = blockIdx.x; asm volatile("" : "+s"(t)); return t; }
; DI float lo2f(unsigned v) { return __uint_as_float(v << 16); }
; DI float hi2f(unsigned v) { return __uint_as_float(v & 0xffff0000u); }
; DI float wave_sum(float v) { for (int o = 32; o > 0; o >>= 1) v += __shfl_xor(v, o); return v; }
; DI const float* modvec(PP p, int l, int s, int idx) { return (const float*)(p->ws + S_MOD) + ((size_t)(l * 5 + s) * 6 + idx) * DM; }
; DI void phase_rowwise(PP p, bool first, const u16* src, const float* g_post, int l_res, int gate_idx,
;                       bool write_h, const float* g_pre, int l_mod, int shift_idx, int scale_idx, bool skip_ctx) {
;   const int lane = get_tid() & 63, w = get_tid() >> 6;
;   u16* H = (u16*)(p->ws + H_OFF);
;   for (int r = get_bid() * 4 + w; r < ROWS; r += gridDim.x * 4) {
;     int b = r / TT, t = r - b * TT;
;     if (skip_ctx && t < CTX) continue;
;     int s = t < CTX ? 4 : b;
;     const float* xin = xrow_in(p, r, first);
;     float x[16];
; #pragma unroll
;     for (int i = 0; i < 4; ++i) { F4 v = *(const F4*)(xin + i * 256 + lane * 4); x[4 * i] = v.x; x[4 * i + 1] = v.y; x[4 * i + 2] = v.z; x[4 * i + 3] = v.w; }
;     if (src) {
;       float y[16]; float ss = 0.f;
; #pragma unroll
;       for (int i = 0; i < 4; ++i) { U2 v = *(const U2*)(src + (size_t)r * DM + i * 256 + lane * 4);
;         y[4 * i] = lo2f(v.x); y[4 * i + 1] = hi2f(v.x); y[4 * i + 2] = lo2f(v.y); y[4 * i + 3] = hi2f(v.y); }
; #pragma unroll
;       for (int i = 0; i < 16; ++i) ss += y[i] * y[i];
;       ss = wave_sum(ss);
;       float rstd = rsqrtf(ss * (1.f / DM) + EPS);
;       const float* gate = modvec(p, l_res, s, gate_idx);
;       float* xo = xrow_out(p, r);
; DI void run_phase(PP p, int ph, unsigned char* lds) {
;     ...
;     case 20: phase_rowwise(p, false, (const u16*)(ws + A_F), p->in[I_NFPOST] + l * DM, l, 5, !last, p->in[I_NMPRE] + (last ? 0 : (l + 1) * DM), last ? l : l + 1, 0, 1, last); break;
.LBB0_76:
	s_mul_hi_i32 s0, s42, 0x30c30c31
	s_lshr_b32 s1, s0, 31
	s_ashr_i32 s0, s0, 2
	s_add_i32 s4, s0, s1
	s_mov_b32 s0, s4
	v_writelane_b32 v251, s0, 31
	v_readlane_b32 s2, v249, 1
	v_readlane_b32 s3, v249, 2
	v_writelane_b32 v251, s1, 32
	s_mul_i32 s0, s4, 21
	s_sub_i32 s1, s42, s0
	v_writelane_b32 v251, s42, 33
	s_sub_i32 s0, s42, 21
	s_cmp_lt_u32 s0, 21
	v_writelane_b32 v251, s43, 34
	v_writelane_b32 v251, s2, 35
	s_load_dwordx2 s[48:49], s[2:3], 0x150
	s_cselect_b64 s[26:27], -1, 0
	s_cmp_gt_u32 s0, 20
	v_writelane_b32 v251, s3, 36
	s_cselect_b64 s[4:5], -1, 0
	s_waitcnt lgkmcnt(0)
	s_add_u32 s2, s48, 0x3900000
	s_addc_u32 s3, s49, 0
	v_writelane_b32 v251, s2, 37
	s_cmp_lt_i32 s1, 10
	s_nop 0
	v_writelane_b32 v251, s3, 38
	v_writelane_b32 v251, s1, 39
	s_mov_b64 s[0:1], -1
	s_cbranch_scc1 .LBB0_603
	v_readlane_b32 s0, v251, 39
	s_cmp_lt_i32 s0, 15
	s_mov_b64 s[0:1], -1
	s_cbranch_scc1 .LBB0_267
	v_readlane_b32 s0, v251, 39
	s_cmp_lt_i32 s0, 18
	s_mov_b64 s[0:1], -1
	s_cbranch_scc1 .LBB0_182
	v_readlane_b32 s0, v251, 39
	s_cmp_lt_i32 s0, 19
	s_mov_b64 s[0:1], -1
	s_cbranch_scc1 .LBB0_142
	v_readlane_b32 s0, v251, 39
	s_cmp_lt_i32 s0, 20
	s_mov_b64 s[0:1], -1
	s_cbranch_scc1 .LBB0_98
	v_readlane_b32 s0, v251, 39
	s_cmp_eq_u32 s0, 20
	s_cbranch_scc0 .LBB0_97
	v_lshrrev_b32_e32 v0, 6, v163
	v_readlane_b32 s2, v249, 0
	v_readfirstlane_b32 s3, v0
	v_and_b32_e32 v0, 63, v163
	s_lshl_b32 s0, s2, 2
	s_add_i32 s0, s0, s3
	v_lshlrev_b32_e32 v2, 4, v0
	v_lshlrev_b32_e32 v3, 3, v0
	v_xor_b32_e32 v4, 32, v0
	v_xor_b32_e32 v5, 16, v0
	v_xor_b32_e32 v6, 8, v0
	v_xor_b32_e32 v7, 4, v0
	v_xor_b32_e32 v8, 2, v0
	v_xor_b32_e32 v9, 1, v0
	v_lshlrev_b32_e32 v4, 2, v4
	v_lshlrev_b32_e32 v5, 2, v5
	v_lshlrev_b32_e32 v6, 2, v6
	v_lshlrev_b32_e32 v7, 2, v7
	v_lshlrev_b32_e32 v8, 2, v8
	v_lshlrev_b32_e32 v9, 2, v9
	v_mov_b32_e32 v75, 0
	v_mov_b32_e32 v229, 0
	v_readlane_b32 s18, v251, 35
	v_readlane_b32 s19, v251, 36
	v_readlane_b32 s10, v251, 31
	s_load_dwordx2 s[6:7], s[18:19], 0x48
	s_load_dwordx2 s[8:9], s[18:19], 0x30
	s_load_dwordx2 s[12:13], s[18:19], 0x148
	s_load_dwordx2 s[14:15], s[18:19], 0x0
	s_lshl_b32 s11, s10, 12
	s_waitcnt lgkmcnt(0)
	s_add_u32 s6, s6, s11
	s_addc_u32 s7, s7, 0
	v_mov_b32_e32 v74, v2
	v_lshl_add_u64 v[170:171], s[6:7], 0, v[74:75]
	s_add_i32 s2, s11, 0x1000
	s_cmp_eq_u32 s10, 1
	s_cselect_b32 s2, 0, s2
	s_add_u32 s8, s8, s2
	s_addc_u32 s9, s9, 0
	v_lshl_add_u64 v[172:173], s[8:9], 0, v[74:75]
	v_mov_b32_e32 v230, s12
	v_mov_b32_e32 v231, s13
	s_add_u32 s2, s48, 0x3330300
	s_addc_u32 s3, s49, 0
	v_mov_b32_e32 v232, s2
	v_mov_b32_e32 v233, s3
	v_mov_b32_e32 v234, s12
	v_mov_b32_e32 v235, s13
	v_mov_b32_e32 v236, s2
	v_mov_b32_e32 v237, s3
	s_add_u32 s6, s48, 0x2b00000
	s_addc_u32 s7, s49, 0
	s_mul_i32 s2, s10, 0x1e000
	s_add_i32 s3, s2, 0x1e000
	s_cmp_eq_u32 s10, 1
	s_cselect_b32 s3, s2, s3
	s_add_u32 s8, s6, s2
	s_addc_u32 s9, s7, 0
	s_add_u32 s8, s8, 0x5000
	s_addc_u32 s9, s9, 0
	v_lshl_add_u64 v[174:175], s[8:9], 0, v[74:75]
	s_add_u32 s8, s6, s3
	s_addc_u32 s9, s7, 0
	s_add_u32 s12, s8, 0x0
	s_addc_u32 s13, s9, 0
	v_lshl_add_u64 v[176:177], s[12:13], 0, v[74:75]
	s_add_u32 s12, s8, 0x1000
	s_addc_u32 s13, s9, 0
	v_lshl_add_u64 v[178:179], s[12:13], 0, v[74:75]
	v_mov_b32_e32 v74, v3
	s_add_u32 s8, s48, 0x13100000
	s_addc_u32 s9, s49, 0
	v_lshl_add_u64 v[180:181], s[8:9], 0, v[74:75]
	s_add_u32 s8, s48, 0x3900000
	s_addc_u32 s9, s49, 0
	v_lshl_add_u64 v[182:183], s[8:9], 0, v[74:75]
	s_cmp_eq_u32 s10, 1
	s_cselect_b32 s11, 1, 0
.Lrw20_first_chk:
	s_cmp_ge_u32 s0, 0x8400
	s_cbranch_scc1 .Lrw20_first_none
	s_cmp_ge_u32 s0, 0x2100
	s_cselect_b32 s2, 1, 0
	s_cmp_ge_u32 s0, 0x4200
	s_addc_u32 s2, s2, 0
	s_cmp_ge_u32 s0, 0x6300
	s_addc_u32 s2, s2, 0
	s_mul_i32 s3, s2, 0x2100
	s_sub_i32 s3, s0, s3
	s_cmp_lt_u32 s3, 0x100
	s_cselect_b32 s6, 1, 0
	s_and_b32 s7, s6, s11
	s_cmp_eq_u32 s7, 0
	s_cbranch_scc1 .Lrw20_first_ok
	s_add_i32 s0, s0, s90
	s_branch .Lrw20_first_chk
.Lrw20_first_ok:
	s_lshl_b32 s7, s2, 8
	s_add_i32 s7, s7, s3
	s_lshl_b32 s12, s2, 13
	s_add_i32 s12, s12, s3
	s_add_i32 s12, s12, 0xffffff00
	s_cmp_eq_u32 s6, 1
	s_cselect_b32 s7, s7, s12
	s_cselect_b32 s9, 4, s2
	s_cselect_b64 s[12:13], -1, 0
	s_lshl_b32 s7, s7, 12
	v_add_u32_e32 v74, s7, v2
	v_cndmask_b32_e64 v0, v234, v236, s[12:13]
	v_cndmask_b32_e64 v227, v235, v237, s[12:13]
	v_mov_b32_e32 v190, v0
	v_mov_b32_e32 v191, v227
	v_lshl_add_u64 v[190:191], v[190:191], 0, v[74:75]
	v_cndmask_b32_e64 v192, v230, v232, s[12:13]
	v_cndmask_b32_e64 v193, v231, v233, s[12:13]
	v_lshl_add_u64 v[192:193], v[192:193], 0, v[74:75]
	s_lshl_b32 s7, s0, 11
	v_mov_b32_e32 v74, s7
	v_lshl_add_u64 v[196:197], v[180:181], 0, v[74:75]
	global_load_dwordx4 v[26:29], v[190:191], off
	global_load_dwordx4 v[30:33], v[190:191], off offset:1024
	global_load_dwordx4 v[34:37], v[190:191], off offset:2048
	global_load_dwordx4 v[38:41], v[190:191], off offset:3072
	global_load_dwordx2 v[42:43], v[196:197], off
	global_load_dwordx2 v[44:45], v[196:197], off offset:512
	global_load_dwordx2 v[46:47], v[196:197], off offset:1024
	global_load_dwordx2 v[48:49], v[196:197], off offset:1536
	s_waitcnt vmcnt(0)
	s_branch .Lrw20_loop

; DI int get_bid() { int t = blockIdx.x; asm volatile("" : "+s"(t)); return t; }
; DI const float* modvec(PP p, int l, int s, int idx) { return (const float*)(p->ws + S_MOD) + ((size_t)(l * 5 + s) * 6 + idx) * DM; }
; DI void phase_rowwise(PP p, bool first, const u16* src, const float* g_post, int l_res, int gate_idx,
;                       bool write_h, const float* g_pre, int l_mod, int shift_idx, int scale_idx, bool skip_ctx) {
;     ...
;   for (int r = get_bid() * 4 + w; r < ROWS; r += gridDim.x * 4) {
;     int b = r / TT, t = r - b * TT;
;     if (skip_ctx && t < CTX) continue;
;     int s = t < CTX ? 4 : b;
;     const float* xin = xrow_in(p, r, first);
;     float x[16];
; #pragma unroll
;     for (int i = 0; i < 4; ++i) { F4 v = *(const F4*)(xin + i * 256 + lane * 4); x[4 * i] = v.x; x[4 * i + 1] = v.y; x[4 * i + 2] = v.z; x[4 * i + 3] = v.w; }
;     ...
;       const float* gate = modvec(p, l_res, s, gate_idx);
;       float* xo = xrow_out(p, r);
; #pragma unroll
;       for (int i = 0; i < 4; ++i) {
;         int k = i * 256 + lane * 4;
;         F4 g = *(const F4*)(g_post + k); F4 gt = *(const F4*)(gate + k);
.Lrw20_loop:
	v_mov_b32_e32 v10, v26
	v_mov_b32_e32 v11, v27
	v_mov_b32_e32 v12, v28
	v_mov_b32_e32 v13, v29
	v_mov_b32_e32 v14, v30
	v_mov_b32_e32 v15, v31
	v_mov_b32_e32 v16, v32
	v_mov_b32_e32 v17, v33
	v_mov_b32_e32 v18, v34
	v_mov_b32_e32 v19, v35
	v_mov_b32_e32 v20, v36
	v_mov_b32_e32 v21, v37
	v_mov_b32_e32 v22, v38
	v_mov_b32_e32 v23, v39
	v_mov_b32_e32 v24, v40
	v_mov_b32_e32 v25, v41
	v_mov_b32_e32 v50, v42
	v_mov_b32_e32 v51, v43
	v_mov_b32_e32 v52, v44
	v_mov_b32_e32 v53, v45
	v_mov_b32_e32 v54, v46
	v_mov_b32_e32 v55, v47
	v_mov_b32_e32 v56, v48
	v_mov_b32_e32 v57, v49
	v_mov_b32_e32 v188, v192
	v_mov_b32_e32 v189, v193
	s_mov_b32 s8, s9
	s_mul_i32 s7, s8, 0x6000
	v_mov_b32_e32 v74, s7
	v_lshl_add_u64 v[220:221], v[174:175], 0, v[74:75]
	v_lshl_add_u64 v[222:223], v[176:177], 0, v[74:75]
	v_lshl_add_u64 v[224:225], v[178:179], 0, v[74:75]
	s_lshl_b32 s7, s0, 11
	v_mov_b32_e32 v74, s7
	v_lshl_add_u64 v[218:219], v[182:183], 0, v[74:75]
	global_load_dwordx4 v[118:121], v[170:171], off
	global_load_dwordx4 v[122:125], v[170:171], off offset:1024
	global_load_dwordx4 v[126:129], v[170:171], off offset:2048
	global_load_dwordx4 v[130:133], v[170:171], off offset:3072
	global_load_dwordx4 v[134:137], v[220:221], off
	global_load_dwordx4 v[138:141], v[220:221], off offset:1024
	global_load_dwordx4 v[142:145], v[220:221], off offset:2048
	global_load_dwordx4 v[146:149], v[220:221], off offset:3072
	s_add_i32 s1, s0, s90
	s_mov_b32 s14, 0
.Lrw20_nxt_chk:
	s_cmp_ge_u32 s1, 0x8400
	s_cbranch_scc1 .Lrw20_nxt_none
	s_cmp_ge_u32 s1, 0x2100
	s_cselect_b32 s2, 1, 0
	s_cmp_ge_u32 s1, 0x4200
	s_addc_u32 s2, s2, 0
	s_cmp_ge_u32 s1, 0x6300
	s_addc_u32 s2, s2, 0
	s_mul_i32 s3, s2, 0x2100
	s_sub_i32 s3, s1, s3
	s_cmp_lt_u32 s3, 0x100
	s_cselect_b32 s6, 1, 0
	s_and_b32 s7, s6, s11
	s_cmp_eq_u32 s7, 0
	s_cbranch_scc1 .Lrw20_nxt_ok
	s_add_i32 s1, s1, s90
	s_branch .Lrw20_nxt_chk

; DI float lo2f(unsigned v) { return __uint_as_float(v << 16); }
; DI float hi2f(unsigned v) { return __uint_as_float(v & 0xffff0000u); }
; DI float wave_sum(float v) { for (int o = 32; o > 0; o >>= 1) v += __shfl_xor(v, o); return v; }
; DI const float* modvec(PP p, int l, int s, int idx) { return (const float*)(p->ws + S_MOD) + ((size_t)(l * 5 + s) * 6 + idx) * DM; }
; DI void phase_rowwise(PP p, bool first, const u16* src, const float* g_post, int l_res, int gate_idx,
;                       bool write_h, const float* g_pre, int l_mod, int shift_idx, int scale_idx, bool skip_ctx) {
;     ...
;     if (src) {
;       float y[16]; float ss = 0.f;
; #pragma unroll
;       for (int i = 0; i < 4; ++i) { U2 v = *(const U2*)(src + (size_t)r * DM + i * 256 + lane * 4);
;         y[4 * i] = lo2f(v.x); y[4 * i + 1] = hi2f(v.x); y[4 * i + 2] = lo2f(v.y); y[4 * i + 3] = hi2f(v.y); }
; #pragma unroll
;       for (int i = 0; i < 16; ++i) ss += y[i] * y[i];
;       ss = wave_sum(ss);
;       float rstd = rsqrtf(ss * (1.f / DM) + EPS);
;       const float* gate = modvec(p, l_res, s, gate_idx);
;       float* xo = xrow_out(p, r);
; #pragma unroll
;       for (int i = 0; i < 4; ++i) {
;         int k = i * 256 + lane * 4;
;         F4 g = *(const F4*)(g_post + k); F4 gt = *(const F4*)(gate + k);
;         x[4 * i] += gt.x * (y[4 * i] * rstd * g.x); x[4 * i + 1] += gt.y * (y[4 * i + 1] * rstd * g.y);
;         x[4 * i + 2] += gt.z * (y[4 * i + 2] * rstd * g.z); x[4 * i + 3] += gt.w * (y[4 * i + 3] * rstd * g.w);
;         *(F4*)(xo + k) = mkf4(x[4 * i], x[4 * i + 1], x[4 * i + 2], x[4 * i + 3]);
.Lrw20_nxt_none:
	s_mov_b32 s14, 1
	s_mov_b32 s1, s0
	s_cmp_ge_u32 s1, 0x2100
	s_cselect_b32 s2, 1, 0
	s_cmp_ge_u32 s1, 0x4200
	s_addc_u32 s2, s2, 0
	s_cmp_ge_u32 s1, 0x6300
	s_addc_u32 s2, s2, 0
	s_mul_i32 s3, s2, 0x2100
	s_sub_i32 s3, s1, s3
	s_cmp_lt_u32 s3, 0x100
	s_cselect_b32 s6, 1, 0
.Lrw20_nxt_go:
	s_lshl_b32 s7, s2, 8
	s_add_i32 s7, s7, s3
	s_lshl_b32 s12, s2, 13
	s_add_i32 s12, s12, s3
	s_add_i32 s12, s12, 0xffffff00
	s_cmp_eq_u32 s6, 1
	s_cselect_b32 s7, s7, s12
	s_cselect_b32 s9, 4, s2
	s_cselect_b64 s[12:13], -1, 0
	s_lshl_b32 s7, s7, 12
	v_add_u32_e32 v74, s7, v2
	v_cndmask_b32_e64 v0, v234, v236, s[12:13]
	v_cndmask_b32_e64 v227, v235, v237, s[12:13]
	v_mov_b32_e32 v190, v0
	v_mov_b32_e32 v191, v227
	v_lshl_add_u64 v[190:191], v[190:191], 0, v[74:75]
	v_cndmask_b32_e64 v192, v230, v232, s[12:13]
	v_cndmask_b32_e64 v193, v231, v233, s[12:13]
	v_lshl_add_u64 v[192:193], v[192:193], 0, v[74:75]
	s_lshl_b32 s7, s1, 11
	v_mov_b32_e32 v74, s7
	v_lshl_add_u64 v[196:197], v[180:181], 0, v[74:75]
	global_load_dwordx4 v[26:29], v[190:191], off
	global_load_dwordx4 v[30:33], v[190:191], off offset:1024
	global_load_dwordx4 v[34:37], v[190:191], off offset:2048
	global_load_dwordx4 v[38:41], v[190:191], off offset:3072
	global_load_dwordx2 v[42:43], v[196:197], off
	global_load_dwordx2 v[44:45], v[196:197], off offset:512
	global_load_dwordx2 v[46:47], v[196:197], off offset:1024
	global_load_dwordx2 v[48:49], v[196:197], off offset:1536
	v_lshlrev_b32_e32 v58, 16, v50
	v_and_b32_e32 v59, 0xffff0000, v50
	v_lshlrev_b32_e32 v60, 16, v51
	v_and_b32_e32 v61, 0xffff0000, v51
	v_lshlrev_b32_e32 v62, 16, v52
	v_and_b32_e32 v63, 0xffff0000, v52
	v_lshlrev_b32_e32 v64, 16, v53
	v_and_b32_e32 v65, 0xffff0000, v53
	v_lshlrev_b32_e32 v66, 16, v54
	v_and_b32_e32 v67, 0xffff0000, v54
	v_lshlrev_b32_e32 v68, 16, v55
	v_and_b32_e32 v69, 0xffff0000, v55
	v_lshlrev_b32_e32 v70, 16, v56
	v_and_b32_e32 v71, 0xffff0000, v56
	v_lshlrev_b32_e32 v72, 16, v57
	v_and_b32_e32 v73, 0xffff0000, v57
	v_mul_f32_e32 v226, v58, v58
	v_mul_f32_e32 v227, v59, v59
	v_add_f32_e32 v226, v226, v227
	v_mul_f32_e32 v227, v60, v60
	v_add_f32_e32 v226, v227, v226
	v_mul_f32_e32 v227, v61, v61
	v_add_f32_e32 v226, v227, v226
	v_mul_f32_e32 v227, v62, v62
	v_add_f32_e32 v226, v227, v226
	v_mul_f32_e32 v227, v63, v63
	v_add_f32_e32 v226, v227, v226
	v_mul_f32_e32 v227, v64, v64
	v_add_f32_e32 v226, v227, v226
	v_mul_f32_e32 v227, v65, v65
	v_add_f32_e32 v226, v227, v226
	v_mul_f32_e32 v227, v66, v66
	v_add_f32_e32 v226, v227, v226
	v_mul_f32_e32 v227, v67, v67
	v_add_f32_e32 v226, v227, v226
	v_mul_f32_e32 v227, v68, v68
	v_add_f32_e32 v226, v227, v226
	v_mul_f32_e32 v227, v69, v69
	v_add_f32_e32 v226, v227, v226
	v_mul_f32_e32 v227, v70, v70
	v_add_f32_e32 v226, v227, v226
	v_mul_f32_e32 v227, v71, v71
	v_add_f32_e32 v226, v227, v226
	v_mul_f32_e32 v227, v72, v72
	v_add_f32_e32 v226, v227, v226
	v_mul_f32_e32 v227, v73, v73
	v_add_f32_e32 v226, v227, v226
	ds_bpermute_b32 v227, v4, v226
	s_waitcnt lgkmcnt(0)
	v_add_f32_e32 v226, v226, v227
	ds_bpermute_b32 v227, v5, v226
	s_waitcnt lgkmcnt(0)
	v_add_f32_e32 v226, v226, v227
	ds_bpermute_b32 v227, v6, v226
	s_waitcnt lgkmcnt(0)
	v_add_f32_e32 v226, v226, v227
	ds_bpermute_b32 v227, v7, v226
	s_waitcnt lgkmcnt(0)
	v_add_f32_e32 v226, v226, v227
	ds_bpermute_b32 v227, v8, v226
	s_waitcnt lgkmcnt(0)
	v_add_f32_e32 v226, v226, v227
	ds_bpermute_b32 v227, v9, v226
	s_waitcnt lgkmcnt(0)
	v_add_f32_e32 v226, v226, v227
	v_fmamk_f32 v226, v226, 0x3a800000, v162
	s_mov_b32 s7, 0x800000
	v_cmp_gt_f32_e32 vcc, s7, v226
	v_mul_f32_e32 v227, 0x4b800000, v226
	s_nop 0
	v_cndmask_b32_e32 v226, v226, v227, vcc
	v_rsq_f32_e32 v226, v226
	s_nop 0
	v_mul_f32_e32 v227, 0x45800000, v226
	v_cndmask_b32_e32 v228, v226, v227, vcc
	s_waitcnt vmcnt(8)
	v_pk_mul_f32 v[58:59], v[228:229], v[58:59] op_sel_hi:[0,1]
	v_pk_mul_f32 v[58:59], v[58:59], v[118:119]
	v_pk_fma_f32 v[10:11], v[134:135], v[58:59], v[10:11]
	v_pk_mul_f32 v[60:61], v[228:229], v[60:61] op_sel_hi:[0,1]
	v_pk_mul_f32 v[60:61], v[60:61], v[120:121]
	v_pk_fma_f32 v[12:13], v[136:137], v[60:61], v[12:13]
	v_pk_mul_f32 v[62:63], v[228:229], v[62:63] op_sel_hi:[0,1]
	v_pk_mul_f32 v[62:63], v[62:63], v[122:123]
	v_pk_fma_f32 v[14:15], v[138:139], v[62:63], v[14:15]
	v_pk_mul_f32 v[64:65], v[228:229], v[64:65] op_sel_hi:[0,1]
	v_pk_mul_f32 v[64:65], v[64:65], v[124:125]
	v_pk_fma_f32 v[16:17], v[140:141], v[64:65], v[16:17]
	v_pk_mul_f32 v[66:67], v[228:229], v[66:67] op_sel_hi:[0,1]
	v_pk_mul_f32 v[66:67], v[66:67], v[126:127]
	v_pk_fma_f32 v[18:19], v[142:143], v[66:67], v[18:19]
	v_pk_mul_f32 v[68:69], v[228:229], v[68:69] op_sel_hi:[0,1]
	v_pk_mul_f32 v[68:69], v[68:69], v[128:129]
	v_pk_fma_f32 v[20:21], v[144:145], v[68:69], v[20:21]
	v_pk_mul_f32 v[70:71], v[228:229], v[70:71] op_sel_hi:[0,1]
	v_pk_mul_f32 v[70:71], v[70:71], v[130:131]
	v_pk_fma_f32 v[22:23], v[146:147], v[70:71], v[22:23]
	v_pk_mul_f32 v[72:73], v[228:229], v[72:73] op_sel_hi:[0,1]
	v_pk_mul_f32 v[72:73], v[72:73], v[132:133]
	v_pk_fma_f32 v[24:25], v[148:149], v[72:73], v[24:25]
	s_cmp_eq_u32 s10, 1
	s_cbranch_scc1 .Lrw20_noh_st
; DI unsigned pack2(float a, float b) { F2 v = {a, b}; B2 r = __builtin_convertvector(v, B2); return __builtin_bit_cast(unsigned, r); }
; DI float wave_sum(float v) { for (int o = 32; o > 0; o >>= 1) v += __shfl_xor(v, o); return v; }
; DI const float* modvec(PP p, int l, int s, int idx) { return (const float*)(p->ws + S_MOD) + ((size_t)(l * 5 + s) * 6 + idx) * DM; }
; DI void phase_rowwise(PP p, bool first, const u16* src, const float* g_post, int l_res, int gate_idx,
;                       bool write_h, const float* g_pre, int l_mod, int shift_idx, int scale_idx, bool skip_ctx) {
;     ...
;     if (write_h) {
;       float ss = 0.f;
; #pragma unroll
;       for (int i = 0; i < 16; ++i) ss += x[i] * x[i];
;       ss = wave_sum(ss);
;       float rstd = rsqrtf(ss * (1.f / DM) + EPS);
;       const float* sh = modvec(p, l_mod, s, shift_idx); const float* sc = modvec(p, l_mod, s, scale_idx);
; #pragma unroll
;       for (int i = 0; i < 4; ++i) {
;         int k = i * 256 + lane * 4;
;         F4 g = *(const F4*)(g_pre + k); F4 a = *(const F4*)(sh + k); F4 c = *(const F4*)(sc + k);
;         float h0 = x[4 * i] * rstd * g.x * (1.f + c.x) + a.x, h1 = x[4 * i + 1] * rstd * g.y * (1.f + c.y) + a.y;
;         float h2 = x[4 * i + 2] * rstd * g.z * (1.f + c.z) + a.z, h3 = x[4 * i + 3] * rstd * g.w * (1.f + c.w) + a.w;
;         *(U2*)(H + (size_t)r * DM + k) = mku2(pack2(h0, h1), pack2(h2, h3));
;       }
;     }
	global_load_dwordx4 v[118:121], v[172:173], off
	global_load_dwordx4 v[122:125], v[172:173], off offset:1024
	global_load_dwordx4 v[126:129], v[172:173], off offset:2048
	global_load_dwordx4 v[130:133], v[172:173], off offset:3072
	global_load_dwordx4 v[134:137], v[222:223], off
	global_load_dwordx4 v[138:141], v[222:223], off offset:1024
	global_load_dwordx4 v[142:145], v[222:223], off offset:2048
	global_load_dwordx4 v[146:149], v[222:223], off offset:3072
	global_load_dwordx4 v[150:153], v[224:225], off
	global_load_dwordx4 v[154:157], v[224:225], off offset:1024
	global_load_dwordx4 v[158:161], v[224:225], off offset:2048
	global_load_dwordx4 v[166:169], v[224:225], off offset:3072
	global_store_dwordx4 v[188:189], v[10:13], off
	global_store_dwordx4 v[188:189], v[14:17], off offset:1024
	global_store_dwordx4 v[188:189], v[18:21], off offset:2048
	global_store_dwordx4 v[188:189], v[22:25], off offset:3072
	v_mul_f32_e32 v226, v10, v10
	v_mul_f32_e32 v227, v11, v11
	v_add_f32_e32 v226, v226, v227
	v_mul_f32_e32 v227, v12, v12
	v_add_f32_e32 v226, v227, v226
	v_mul_f32_e32 v227, v13, v13
	v_add_f32_e32 v226, v227, v226
	v_mul_f32_e32 v227, v14, v14
	v_add_f32_e32 v226, v227, v226
	v_mul_f32_e32 v227, v15, v15
	v_add_f32_e32 v226, v227, v226
	v_mul_f32_e32 v227, v16, v16
	v_add_f32_e32 v226, v227, v226
	v_mul_f32_e32 v227, v17, v17
	v_add_f32_e32 v226, v227, v226
	v_mul_f32_e32 v227, v18, v18
	v_add_f32_e32 v226, v227, v226
	v_mul_f32_e32 v227, v19, v19
	v_add_f32_e32 v226, v227, v226
	v_mul_f32_e32 v227, v20, v20
	v_add_f32_e32 v226, v227, v226
	v_mul_f32_e32 v227, v21, v21
	v_add_f32_e32 v226, v227, v226
	v_mul_f32_e32 v227, v22, v22
	v_add_f32_e32 v226, v227, v226
	v_mul_f32_e32 v227, v23, v23
	v_add_f32_e32 v226, v227, v226
	v_mul_f32_e32 v227, v24, v24
	v_add_f32_e32 v226, v227, v226
	v_mul_f32_e32 v227, v25, v25
	v_add_f32_e32 v226, v227, v226
	ds_bpermute_b32 v227, v4, v226
	s_waitcnt lgkmcnt(0)
	v_add_f32_e32 v226, v226, v227
	ds_bpermute_b32 v227, v5, v226
	s_waitcnt lgkmcnt(0)
	v_add_f32_e32 v226, v226, v227
	ds_bpermute_b32 v227, v6, v226
	s_waitcnt lgkmcnt(0)
	v_add_f32_e32 v226, v226, v227
	ds_bpermute_b32 v227, v7, v226
	s_waitcnt lgkmcnt(0)
	v_add_f32_e32 v226, v226, v227
	ds_bpermute_b32 v227, v8, v226
	s_waitcnt lgkmcnt(0)
	v_add_f32_e32 v226, v226, v227
	ds_bpermute_b32 v227, v9, v226
	s_waitcnt lgkmcnt(0)
	v_add_f32_e32 v226, v226, v227
	v_fmamk_f32 v226, v226, 0x3a800000, v162
	s_mov_b32 s7, 0x800000
	v_cmp_gt_f32_e32 vcc, s7, v226
	v_mul_f32_e32 v227, 0x4b800000, v226
	s_nop 0
	v_cndmask_b32_e32 v226, v226, v227, vcc
	v_rsq_f32_e32 v226, v226
	s_nop 0
	v_mul_f32_e32 v227, 0x45800000, v226
	v_cndmask_b32_e32 v228, v226, v227, vcc
	s_waitcnt vmcnt(4)
	v_pk_mul_f32 v[10:11], v[10:11], v[228:229] op_sel_hi:[1,0]
	v_pk_mul_f32 v[10:11], v[118:119], v[10:11]
	v_pk_add_f32 v[58:59], v[150:151], 1.0 op_sel_hi:[1,0]
	s_nop 0
	v_pk_fma_f32 v[10:11], v[58:59], v[10:11], v[134:135]
	v_pk_mul_f32 v[12:13], v[12:13], v[228:229] op_sel_hi:[1,0]
	v_pk_mul_f32 v[12:13], v[120:121], v[12:13]
	v_pk_add_f32 v[60:61], v[152:153], 1.0 op_sel_hi:[1,0]
	s_nop 0
	v_pk_fma_f32 v[12:13], v[60:61], v[12:13], v[136:137]
	v_cvt_pk_bf16_f32 v66, v10, v11
	v_cvt_pk_bf16_f32 v67, v12, v13
	global_store_dwordx2 v[218:219], v[66:67], off
	s_nop 1
	v_pk_mul_f32 v[14:15], v[14:15], v[228:229] op_sel_hi:[1,0]
	v_pk_mul_f32 v[14:15], v[122:123], v[14:15]
	v_pk_add_f32 v[58:59], v[154:155], 1.0 op_sel_hi:[1,0]
	s_nop 0
	v_pk_fma_f32 v[14:15], v[58:59], v[14:15], v[138:139]
	v_pk_mul_f32 v[16:17], v[16:17], v[228:229] op_sel_hi:[1,0]
	v_pk_mul_f32 v[16:17], v[124:125], v[16:17]
	v_pk_add_f32 v[60:61], v[156:157], 1.0 op_sel_hi:[1,0]
	s_nop 0
	v_pk_fma_f32 v[16:17], v[60:61], v[16:17], v[140:141]
	v_cvt_pk_bf16_f32 v66, v14, v15
	v_cvt_pk_bf16_f32 v67, v16, v17
	global_store_dwordx2 v[218:219], v[66:67], off offset:512
	s_nop 1
	v_pk_mul_f32 v[18:19], v[18:19], v[228:229] op_sel_hi:[1,0]
	v_pk_mul_f32 v[18:19], v[126:127], v[18:19]
	v_pk_add_f32 v[58:59], v[158:159], 1.0 op_sel_hi:[1,0]
	s_nop 0
	v_pk_fma_f32 v[18:19], v[58:59], v[18:19], v[142:143]
	v_pk_mul_f32 v[20:21], v[20:21], v[228:229] op_sel_hi:[1,0]
	v_pk_mul_f32 v[20:21], v[128:129], v[20:21]
	v_pk_add_f32 v[60:61], v[160:161], 1.0 op_sel_hi:[1,0]
	s_nop 0
	v_pk_fma_f32 v[20:21], v[60:61], v[20:21], v[144:145]
	v_cvt_pk_bf16_f32 v66, v18, v19
	v_cvt_pk_bf16_f32 v67, v20, v21
	global_store_dwordx2 v[218:219], v[66:67], off offset:1024
	s_nop 1
	v_pk_mul_f32 v[22:23], v[22:23], v[228:229] op_sel_hi:[1,0]
	v_pk_mul_f32 v[22:23], v[130:131], v[22:23]
	v_pk_add_f32 v[58:59], v[166:167], 1.0 op_sel_hi:[1,0]
	s_nop 0
	v_pk_fma_f32 v[22:23], v[58:59], v[22:23], v[146:147]
	v_pk_mul_f32 v[24:25], v[24:25], v[228:229] op_sel_hi:[1,0]
	v_pk_mul_f32 v[24:25], v[132:133], v[24:25]
	v_pk_add_f32 v[60:61], v[168:169], 1.0 op_sel_hi:[1,0]
	s_nop 0
	v_pk_fma_f32 v[24:25], v[60:61], v[24:25], v[148:149]
	v_cvt_pk_bf16_f32 v66, v22, v23
	v_cvt_pk_bf16_f32 v67, v24, v25
	global_store_dwordx2 v[218:219], v[66:67], off offset:1536
	s_nop 1
	s_branch .Lrw20_noh
.Lrw20_noh_st:
	global_store_dwordx4 v[188:189], v[10:13], off
	global_store_dwordx4 v[188:189], v[14:17], off offset:1024
	global_store_dwordx4 v[188:189], v[18:21], off offset:2048
	global_store_dwordx4 v[188:189], v[22:25], off offset:3072
	s_waitcnt vmcnt(4)
.Lrw20_noh:
	s_cmp_eq_u32 s14, 1
	s_cbranch_scc1 .Lrw20_done
	s_mov_b32 s0, s1
	s_branch .Lrw20_loop
.Lrw20_done:
	s_waitcnt vmcnt(0)
.LBB0_96:
	s_or_b64 exec, exec, s[6:7]

; DI int get_tid() { int t = threadIdx.x; asm volatile("" : "+v"(t)); return t; }
; DI int get_bid() { int t = blockIdx.x; asm volatile("" : "+s"(t)); return t; }
; DI void phase_rowwise(PP p, bool first, const u16* src, const float* g_post, int l_res, int gate_idx,
;                       bool write_h, const float* g_pre, int l_mod, int shift_idx, int scale_idx, bool skip_ctx) {
;   const int lane = get_tid() & 63, w = get_tid() >> 6;
;   u16* H = (u16*)(p->ws + H_OFF);
;   for (int r = get_bid() * 4 + w; r < ROWS; r += gridDim.x * 4) {
;     int b = r / TT, t = r - b * TT;
;     if (skip_ctx && t < CTX) continue;
;     int s = t < CTX ? 4 : b;
;     const float* xin = xrow_in(p, r, first);
;     float x[16];
; #pragma unroll
;     for (int i = 0; i < 4; ++i) { F4 v = *(const F4*)(xin + i * 256 + lane * 4); x[4 * i] = v.x; x[4 * i + 1] = v.y; x[4 * i + 2] = v.z; x[4 * i + 3] = v.w; }
; DI void run_phase(PP p, int ph, unsigned char* lds) {
;     ...
;     case 17: phase_rowwise(p, l == 0, (const u16*)(ws + A_YOUT), p->in[I_NMPOST] + l * DM, l, 2, true, p->in[I_NFPRE] + l * DM, l, 3, 4, last); break;
.LBB0_182:
	s_andn2_b64 vcc, exec, s[0:1]
	s_cbranch_vccnz .LBB0_266
	v_readlane_b32 s0, v251, 39
	s_cmp_lt_i32 s0, 16
	s_mov_b64 s[0:1], -1
	s_cbranch_scc1 .LBB0_249
	v_readlane_b32 s0, v251, 39
	s_cmp_gt_i32 s0, 16
	s_mov_b64 s[0:1], -1
	s_cbranch_scc0 .LBB0_207
	v_lshrrev_b32_e32 v0, 6, v163
	v_readlane_b32 s2, v249, 0
	v_readfirstlane_b32 s3, v0
	v_and_b32_e32 v0, 63, v163
	s_lshl_b32 s0, s2, 2
	s_add_i32 s0, s0, s3
	v_lshlrev_b32_e32 v2, 4, v0
	v_lshlrev_b32_e32 v3, 3, v0
	v_xor_b32_e32 v4, 32, v0
	v_xor_b32_e32 v5, 16, v0
	v_xor_b32_e32 v6, 8, v0
	v_xor_b32_e32 v7, 4, v0
	v_xor_b32_e32 v8, 2, v0
	v_xor_b32_e32 v9, 1, v0
	v_lshlrev_b32_e32 v4, 2, v4
	v_lshlrev_b32_e32 v5, 2, v5
	v_lshlrev_b32_e32 v6, 2, v6
	v_lshlrev_b32_e32 v7, 2, v7
	v_lshlrev_b32_e32 v8, 2, v8
	v_lshlrev_b32_e32 v9, 2, v9
	v_mov_b32_e32 v75, 0
	v_mov_b32_e32 v229, 0
	v_readlane_b32 s18, v251, 35
	v_readlane_b32 s19, v251, 36
	v_readlane_b32 s10, v251, 31
	s_load_dwordx2 s[6:7], s[18:19], 0x38
	s_load_dwordx2 s[8:9], s[18:19], 0x40
	s_load_dwordx2 s[12:13], s[18:19], 0x148
	s_load_dwordx2 s[14:15], s[18:19], 0x0
	s_lshl_b32 s11, s10, 12
	s_waitcnt lgkmcnt(0)
	s_add_u32 s6, s6, s11
	s_addc_u32 s7, s7, 0
	v_mov_b32_e32 v74, v2
	v_lshl_add_u64 v[170:171], s[6:7], 0, v[74:75]
	s_add_u32 s8, s8, s11
	s_addc_u32 s9, s9, 0
	v_lshl_add_u64 v[172:173], s[8:9], 0, v[74:75]
	v_mov_b32_e32 v230, s12
	v_mov_b32_e32 v231, s13
	s_add_u32 s2, s48, 0x3330300
	s_addc_u32 s3, s49, 0
	v_mov_b32_e32 v232, s2
	v_mov_b32_e32 v233, s3
	s_load_dwordx2 s[6:7], s[18:19], 0x10
	s_waitcnt lgkmcnt(0)
	s_cmp_eq_u32 s10, 0
	s_cselect_b32 s14, s14, s12
	s_cselect_b32 s15, s15, s13
	s_cselect_b32 s6, s6, s2
	s_cselect_b32 s7, s7, s3
	v_mov_b32_e32 v234, s14
	v_mov_b32_e32 v235, s15
	v_mov_b32_e32 v236, s6
	v_mov_b32_e32 v237, s7
	s_add_u32 s6, s48, 0x2b00000
	s_addc_u32 s7, s49, 0
	s_mul_i32 s2, s10, 0x1e000
	s_mov_b32 s3, s2
	s_add_u32 s8, s6, s2
	s_addc_u32 s9, s7, 0
	s_add_u32 s8, s8, 0x2000
	s_addc_u32 s9, s9, 0
	v_lshl_add_u64 v[174:175], s[8:9], 0, v[74:75]
	s_add_u32 s8, s6, s3
	s_addc_u32 s9, s7, 0
	s_add_u32 s12, s8, 0x3000
	s_addc_u32 s13, s9, 0
	v_lshl_add_u64 v[176:177], s[12:13], 0, v[74:75]
	s_add_u32 s12, s8, 0x4000
	s_addc_u32 s13, s9, 0
	v_lshl_add_u64 v[178:179], s[12:13], 0, v[74:75]
	v_mov_b32_e32 v74, v3
	s_add_u32 s8, s48, 0x12000000
	s_addc_u32 s9, s49, 0
	v_lshl_add_u64 v[180:181], s[8:9], 0, v[74:75]
	s_add_u32 s8, s48, 0x3900000
	s_addc_u32 s9, s49, 0
	v_lshl_add_u64 v[182:183], s[8:9], 0, v[74:75]
	s_cmp_eq_u32 s10, 1
	s_cselect_b32 s11, 1, 0

; DI float lo2f(unsigned v) { return __uint_as_float(v << 16); }
; DI float hi2f(unsigned v) { return __uint_as_float(v & 0xffff0000u); }
; DI float wave_sum(float v) { for (int o = 32; o > 0; o >>= 1) v += __shfl_xor(v, o); return v; }
; DI void phase_rowwise(PP p, bool first, const u16* src, const float* g_post, int l_res, int gate_idx,
;                       bool write_h, const float* g_pre, int l_mod, int shift_idx, int scale_idx, bool skip_ctx) {
;     ...
;     if (src) {
;       float y[16]; float ss = 0.f;
; #pragma unroll
;       for (int i = 0; i < 4; ++i) { U2 v = *(const U2*)(src + (size_t)r * DM + i * 256 + lane * 4);
;         y[4 * i] = lo2f(v.x); y[4 * i + 1] = hi2f(v.x); y[4 * i + 2] = lo2f(v.y); y[4 * i + 3] = hi2f(v.y); }
; #pragma unroll
;       for (int i = 0; i < 16; ++i) ss += y[i] * y[i];
;       ss = wave_sum(ss);
;       float rstd = rsqrtf(ss * (1.f / DM) + EPS);
.Lrw17_nxt_go:
	s_lshl_b32 s7, s2, 8
	s_add_i32 s7, s7, s3
	s_lshl_b32 s12, s2, 13
	s_add_i32 s12, s12, s3
	s_add_i32 s12, s12, 0xffffff00
	s_cmp_eq_u32 s6, 1
	s_cselect_b32 s7, s7, s12
	s_cselect_b32 s9, 4, s2
	s_cselect_b64 s[12:13], -1, 0
	s_lshl_b32 s7, s7, 12
	v_add_u32_e32 v74, s7, v2
	v_cndmask_b32_e64 v0, v234, v236, s[12:13]
	v_cndmask_b32_e64 v227, v235, v237, s[12:13]
	v_mov_b32_e32 v190, v0
	v_mov_b32_e32 v191, v227
	v_lshl_add_u64 v[190:191], v[190:191], 0, v[74:75]
	v_cndmask_b32_e64 v192, v230, v232, s[12:13]
	v_cndmask_b32_e64 v193, v231, v233, s[12:13]
	v_lshl_add_u64 v[192:193], v[192:193], 0, v[74:75]
	s_lshl_b32 s7, s1, 11
	v_mov_b32_e32 v74, s7
	v_lshl_add_u64 v[196:197], v[180:181], 0, v[74:75]
	global_load_dwordx4 v[26:29], v[190:191], off
	global_load_dwordx4 v[30:33], v[190:191], off offset:1024
	global_load_dwordx4 v[34:37], v[190:191], off offset:2048
	global_load_dwordx4 v[38:41], v[190:191], off offset:3072
	global_load_dwordx2 v[42:43], v[196:197], off
	global_load_dwordx2 v[44:45], v[196:197], off offset:512
	global_load_dwordx2 v[46:47], v[196:197], off offset:1024
	global_load_dwordx2 v[48:49], v[196:197], off offset:1536
	v_lshlrev_b32_e32 v58, 16, v50
	v_and_b32_e32 v59, 0xffff0000, v50
	v_lshlrev_b32_e32 v60, 16, v51
	v_and_b32_e32 v61, 0xffff0000, v51
	v_lshlrev_b32_e32 v62, 16, v52
	v_and_b32_e32 v63, 0xffff0000, v52
	v_lshlrev_b32_e32 v64, 16, v53
	v_and_b32_e32 v65, 0xffff0000, v53
	v_lshlrev_b32_e32 v66, 16, v54
	v_and_b32_e32 v67, 0xffff0000, v54
	v_lshlrev_b32_e32 v68, 16, v55
	v_and_b32_e32 v69, 0xffff0000, v55
	v_lshlrev_b32_e32 v70, 16, v56
	v_and_b32_e32 v71, 0xffff0000, v56
	v_lshlrev_b32_e32 v72, 16, v57
	v_and_b32_e32 v73, 0xffff0000, v57
	v_mul_f32_e32 v226, v58, v58
	v_mul_f32_e32 v227, v59, v59
	v_add_f32_e32 v226, v226, v227
	v_mul_f32_e32 v227, v60, v60
	v_add_f32_e32 v226, v227, v226
	v_mul_f32_e32 v227, v61, v61
	v_add_f32_e32 v226, v227, v226
	v_mul_f32_e32 v227, v62, v62
	v_add_f32_e32 v226, v227, v226
	v_mul_f32_e32 v227, v63, v63
	v_add_f32_e32 v226, v227, v226
	v_mul_f32_e32 v227, v64, v64
	v_add_f32_e32 v226, v227, v226
	v_mul_f32_e32 v227, v65, v65
	v_add_f32_e32 v226, v227, v226
	v_mul_f32_e32 v227, v66, v66
	v_add_f32_e32 v226, v227, v226
	v_mul_f32_e32 v227, v67, v67
	v_add_f32_e32 v226, v227, v226
	v_mul_f32_e32 v227, v68, v68
	v_add_f32_e32 v226, v227, v226
	v_mul_f32_e32 v227, v69, v69
	v_add_f32_e32 v226, v227, v226
	v_mul_f32_e32 v227, v70, v70
	v_add_f32_e32 v226, v227, v226
	v_mul_f32_e32 v227, v71, v71
	v_add_f32_e32 v226, v227, v226
	v_mul_f32_e32 v227, v72, v72
	v_add_f32_e32 v226, v227, v226
	v_mul_f32_e32 v227, v73, v73
	v_add_f32_e32 v226, v227, v226
	ds_bpermute_b32 v227, v4, v226
	s_waitcnt lgkmcnt(0)
	v_add_f32_e32 v226, v226, v227
	ds_bpermute_b32 v227, v5, v226
	s_waitcnt lgkmcnt(0)
	v_add_f32_e32 v226, v226, v227
	ds_bpermute_b32 v227, v6, v226
	s_waitcnt lgkmcnt(0)
	v_add_f32_e32 v226, v226, v227
	ds_bpermute_b32 v227, v7, v226
	s_waitcnt lgkmcnt(0)
	v_add_f32_e32 v226, v226, v227
	ds_bpermute_b32 v227, v8, v226
	s_waitcnt lgkmcnt(0)
	v_add_f32_e32 v226, v226, v227
	ds_bpermute_b32 v227, v9, v226
	s_waitcnt lgkmcnt(0)
	v_add_f32_e32 v226, v226, v227
	v_fmamk_f32 v226, v226, 0x3a800000, v162
	s_mov_b32 s7, 0x800000
	v_cmp_gt_f32_e32 vcc, s7, v226
	v_mul_f32_e32 v227, 0x4b800000, v226
	s_nop 0
	v_cndmask_b32_e32 v226, v226, v227, vcc
	v_rsq_f32_e32 v226, v226
	s_nop 0
	v_mul_f32_e32 v227, 0x45800000, v226
	v_cndmask_b32_e32 v228, v226, v227, vcc
	s_waitcnt vmcnt(8)
; DI unsigned pack2(float a, float b) { F2 v = {a, b}; B2 r = __builtin_convertvector(v, B2); return __builtin_bit_cast(unsigned, r); }
; DI float wave_sum(float v) { for (int o = 32; o > 0; o >>= 1) v += __shfl_xor(v, o); return v; }
; DI const float* modvec(PP p, int l, int s, int idx) { return (const float*)(p->ws + S_MOD) + ((size_t)(l * 5 + s) * 6 + idx) * DM; }
; DI void phase_rowwise(PP p, bool first, const u16* src, const float* g_post, int l_res, int gate_idx,
;                       bool write_h, const float* g_pre, int l_mod, int shift_idx, int scale_idx, bool skip_ctx) {
;     ...
; #pragma unroll
;       for (int i = 0; i < 4; ++i) {
;         int k = i * 256 + lane * 4;
;         F4 g = *(const F4*)(g_post + k); F4 gt = *(const F4*)(gate + k);
;         x[4 * i] += gt.x * (y[4 * i] * rstd * g.x); x[4 * i + 1] += gt.y * (y[4 * i + 1] * rstd * g.y);
;         x[4 * i + 2] += gt.z * (y[4 * i + 2] * rstd * g.z); x[4 * i + 3] += gt.w * (y[4 * i + 3] * rstd * g.w);
;         *(F4*)(xo + k) = mkf4(x[4 * i], x[4 * i + 1], x[4 * i + 2], x[4 * i + 3]);
;       }
;     }
;     if (write_h) {
;       float ss = 0.f;
; #pragma unroll
;       for (int i = 0; i < 16; ++i) ss += x[i] * x[i];
;       ss = wave_sum(ss);
;       float rstd = rsqrtf(ss * (1.f / DM) + EPS);
;       const float* sh = modvec(p, l_mod, s, shift_idx); const float* sc = modvec(p, l_mod, s, scale_idx);
; #pragma unroll
;       for (int i = 0; i < 4; ++i) {
;         int k = i * 256 + lane * 4;
;         F4 g = *(const F4*)(g_pre + k); F4 a = *(const F4*)(sh + k); F4 c = *(const F4*)(sc + k);
;         float h0 = x[4 * i] * rstd * g.x * (1.f + c.x) + a.x, h1 = x[4 * i + 1] * rstd * g.y * (1.f + c.y) + a.y;
;         float h2 = x[4 * i + 2] * rstd * g.z * (1.f + c.z) + a.z, h3 = x[4 * i + 3] * rstd * g.w * (1.f + c.w) + a.w;
;         *(U2*)(H + (size_t)r * DM + k) = mku2(pack2(h0, h1), pack2(h2, h3));
;       }
	v_pk_mul_f32 v[58:59], v[228:229], v[58:59] op_sel_hi:[0,1]
	v_pk_mul_f32 v[58:59], v[58:59], v[118:119]
	v_pk_fma_f32 v[10:11], v[134:135], v[58:59], v[10:11]
	v_pk_mul_f32 v[60:61], v[228:229], v[60:61] op_sel_hi:[0,1]
	v_pk_mul_f32 v[60:61], v[60:61], v[120:121]
	v_pk_fma_f32 v[12:13], v[136:137], v[60:61], v[12:13]
	v_pk_mul_f32 v[62:63], v[228:229], v[62:63] op_sel_hi:[0,1]
	v_pk_mul_f32 v[62:63], v[62:63], v[122:123]
	v_pk_fma_f32 v[14:15], v[138:139], v[62:63], v[14:15]
	v_pk_mul_f32 v[64:65], v[228:229], v[64:65] op_sel_hi:[0,1]
	v_pk_mul_f32 v[64:65], v[64:65], v[124:125]
	v_pk_fma_f32 v[16:17], v[140:141], v[64:65], v[16:17]
	v_pk_mul_f32 v[66:67], v[228:229], v[66:67] op_sel_hi:[0,1]
	v_pk_mul_f32 v[66:67], v[66:67], v[126:127]
	v_pk_fma_f32 v[18:19], v[142:143], v[66:67], v[18:19]
	v_pk_mul_f32 v[68:69], v[228:229], v[68:69] op_sel_hi:[0,1]
	v_pk_mul_f32 v[68:69], v[68:69], v[128:129]
	v_pk_fma_f32 v[20:21], v[144:145], v[68:69], v[20:21]
	v_pk_mul_f32 v[70:71], v[228:229], v[70:71] op_sel_hi:[0,1]
	v_pk_mul_f32 v[70:71], v[70:71], v[130:131]
	v_pk_fma_f32 v[22:23], v[146:147], v[70:71], v[22:23]
	v_pk_mul_f32 v[72:73], v[228:229], v[72:73] op_sel_hi:[0,1]
	v_pk_mul_f32 v[72:73], v[72:73], v[132:133]
	v_pk_fma_f32 v[24:25], v[148:149], v[72:73], v[24:25]
	global_load_dwordx4 v[118:121], v[172:173], off
	global_load_dwordx4 v[122:125], v[172:173], off offset:1024
	global_load_dwordx4 v[126:129], v[172:173], off offset:2048
	global_load_dwordx4 v[130:133], v[172:173], off offset:3072
	global_load_dwordx4 v[134:137], v[222:223], off
	global_load_dwordx4 v[138:141], v[222:223], off offset:1024
	global_load_dwordx4 v[142:145], v[222:223], off offset:2048
	global_load_dwordx4 v[146:149], v[222:223], off offset:3072
	global_load_dwordx4 v[150:153], v[224:225], off
	global_load_dwordx4 v[154:157], v[224:225], off offset:1024
	global_load_dwordx4 v[158:161], v[224:225], off offset:2048
	global_load_dwordx4 v[166:169], v[224:225], off offset:3072
	global_store_dwordx4 v[188:189], v[10:13], off
	global_store_dwordx4 v[188:189], v[14:17], off offset:1024
	global_store_dwordx4 v[188:189], v[18:21], off offset:2048
	global_store_dwordx4 v[188:189], v[22:25], off offset:3072
	v_mul_f32_e32 v226, v10, v10
	v_mul_f32_e32 v227, v11, v11
	v_add_f32_e32 v226, v226, v227
	v_mul_f32_e32 v227, v12, v12
	v_add_f32_e32 v226, v227, v226
	v_mul_f32_e32 v227, v13, v13
	v_add_f32_e32 v226, v227, v226
	v_mul_f32_e32 v227, v14, v14
	v_add_f32_e32 v226, v227, v226
	v_mul_f32_e32 v227, v15, v15
	v_add_f32_e32 v226, v227, v226
	v_mul_f32_e32 v227, v16, v16
	v_add_f32_e32 v226, v227, v226
	v_mul_f32_e32 v227, v17, v17
	v_add_f32_e32 v226, v227, v226
	v_mul_f32_e32 v227, v18, v18
	v_add_f32_e32 v226, v227, v226
	v_mul_f32_e32 v227, v19, v19
	v_add_f32_e32 v226, v227, v226
	v_mul_f32_e32 v227, v20, v20
	v_add_f32_e32 v226, v227, v226
	v_mul_f32_e32 v227, v21, v21
	v_add_f32_e32 v226, v227, v226
	v_mul_f32_e32 v227, v22, v22
	v_add_f32_e32 v226, v227, v226
	v_mul_f32_e32 v227, v23, v23
	v_add_f32_e32 v226, v227, v226
	v_mul_f32_e32 v227, v24, v24
	v_add_f32_e32 v226, v227, v226
	v_mul_f32_e32 v227, v25, v25
	v_add_f32_e32 v226, v227, v226
	ds_bpermute_b32 v227, v4, v226
	s_waitcnt lgkmcnt(0)
	v_add_f32_e32 v226, v226, v227
	ds_bpermute_b32 v227, v5, v226
	s_waitcnt lgkmcnt(0)
	v_add_f32_e32 v226, v226, v227
	ds_bpermute_b32 v227, v6, v226
	s_waitcnt lgkmcnt(0)
	v_add_f32_e32 v226, v226, v227
	ds_bpermute_b32 v227, v7, v226
	s_waitcnt lgkmcnt(0)
	v_add_f32_e32 v226, v226, v227
	ds_bpermute_b32 v227, v8, v226
	s_waitcnt lgkmcnt(0)
	v_add_f32_e32 v226, v226, v227
	ds_bpermute_b32 v227, v9, v226
	s_waitcnt lgkmcnt(0)
	v_add_f32_e32 v226, v226, v227
	v_fmamk_f32 v226, v226, 0x3a800000, v162
	s_mov_b32 s7, 0x800000
	v_cmp_gt_f32_e32 vcc, s7, v226
	v_mul_f32_e32 v227, 0x4b800000, v226
	s_nop 0
	v_cndmask_b32_e32 v226, v226, v227, vcc
	v_rsq_f32_e32 v226, v226
	s_nop 0
	v_mul_f32_e32 v227, 0x45800000, v226
	v_cndmask_b32_e32 v228, v226, v227, vcc
	s_waitcnt vmcnt(4)
	v_pk_mul_f32 v[10:11], v[10:11], v[228:229] op_sel_hi:[1,0]
	v_pk_mul_f32 v[10:11], v[118:119], v[10:11]
	v_pk_add_f32 v[58:59], v[150:151], 1.0 op_sel_hi:[1,0]
	s_nop 0
	v_pk_fma_f32 v[10:11], v[58:59], v[10:11], v[134:135]
	v_pk_mul_f32 v[12:13], v[12:13], v[228:229] op_sel_hi:[1,0]
	v_pk_mul_f32 v[12:13], v[120:121], v[12:13]
	v_pk_add_f32 v[60:61], v[152:153], 1.0 op_sel_hi:[1,0]
	s_nop 0
	v_pk_fma_f32 v[12:13], v[60:61], v[12:13], v[136:137]
	v_cvt_pk_bf16_f32 v66, v10, v11
	v_cvt_pk_bf16_f32 v67, v12, v13
	global_store_dwordx2 v[218:219], v[66:67], off
	s_nop 1
	v_pk_mul_f32 v[14:15], v[14:15], v[228:229] op_sel_hi:[1,0]
	v_pk_mul_f32 v[14:15], v[122:123], v[14:15]
	v_pk_add_f32 v[58:59], v[154:155], 1.0 op_sel_hi:[1,0]
	s_nop 0
	v_pk_fma_f32 v[14:15], v[58:59], v[14:15], v[138:139]
	v_pk_mul_f32 v[16:17], v[16:17], v[228:229] op_sel_hi:[1,0]
	v_pk_mul_f32 v[16:17], v[124:125], v[16:17]
	v_pk_add_f32 v[60:61], v[156:157], 1.0 op_sel_hi:[1,0]
	s_nop 0
	v_pk_fma_f32 v[16:17], v[60:61], v[16:17], v[140:141]
	v_cvt_pk_bf16_f32 v66, v14, v15
	v_cvt_pk_bf16_f32 v67, v16, v17
	global_store_dwordx2 v[218:219], v[66:67], off offset:512
	s_nop 1
	v_pk_mul_f32 v[18:19], v[18:19], v[228:229] op_sel_hi:[1,0]
	v_pk_mul_f32 v[18:19], v[126:127], v[18:19]
	v_pk_add_f32 v[58:59], v[158:159], 1.0 op_sel_hi:[1,0]
	s_nop 0
	v_pk_fma_f32 v[18:19], v[58:59], v[18:19], v[142:143]
	v_pk_mul_f32 v[20:21], v[20:21], v[228:229] op_sel_hi:[1,0]
	v_pk_mul_f32 v[20:21], v[128:129], v[20:21]
	v_pk_add_f32 v[60:61], v[160:161], 1.0 op_sel_hi:[1,0]
	s_nop 0
	v_pk_fma_f32 v[20:21], v[60:61], v[20:21], v[144:145]
	v_cvt_pk_bf16_f32 v66, v18, v19
	v_cvt_pk_bf16_f32 v67, v20, v21
	global_store_dwordx2 v[218:219], v[66:67], off offset:1024
	s_nop 1
	v_pk_mul_f32 v[22:23], v[22:23], v[228:229] op_sel_hi:[1,0]
	v_pk_mul_f32 v[22:23], v[130:131], v[22:23]
	v_pk_add_f32 v[58:59], v[166:167], 1.0 op_sel_hi:[1,0]
	s_nop 0
	v_pk_fma_f32 v[22:23], v[58:59], v[22:23], v[146:147]
	v_pk_mul_f32 v[24:25], v[24:25], v[228:229] op_sel_hi:[1,0]
	v_pk_mul_f32 v[24:25], v[132:133], v[24:25]
	v_pk_add_f32 v[60:61], v[168:169], 1.0 op_sel_hi:[1,0]
	s_nop 0
	v_pk_fma_f32 v[24:25], v[60:61], v[24:25], v[148:149]
	v_cvt_pk_bf16_f32 v66, v22, v23
	v_cvt_pk_bf16_f32 v67, v24, v25
	global_store_dwordx2 v[218:219], v[66:67], off offset:1536
	s_nop 1
	s_branch .Lrw17_noh

; DI void phase_rowwise(PP p, bool first, const u16* src, const float* g_post, int l_res, int gate_idx,
;                       bool write_h, const float* g_pre, int l_mod, int shift_idx, int scale_idx, bool skip_ctx) {
;     ...
;   }
; }
.Lrw17_done:
	s_waitcnt vmcnt(0)
.LBB0_206:
	s_or_b64 exec, exec, s[4:5]
	s_mov_b64 s[0:1], 0
